# GEMM mainloop: 4 duplicate post-barrier LDS waits dropped; attention second half: alpha written straight to its final register, scaled-max temp used directly by the packed fma (two copies removed)
# baseline (speedup 1.0000x reference)
; __device__ __forceinline__ void finishSM(f32x16& p0, f32x16& p1, float alpha, float& l_reg, bf16x8& pa0, bf16x8& pa1, bf16x8& pa2, bf16x8& pa3) {
; #pragma unroll
;     for (int r = 0; r < 16; ++r) p1[r] = __builtin_amdgcn_exp2f(p1[r]);
;     float ps = 0;
; #pragma unroll
;     for (int r = 0; r < 16; ++r) ps += p0[r];
; #pragma unroll
;     for (int r = 0; r < 16; ++r) ps += p1[r];
;     { auto rr = __builtin_amdgcn_permlane32_swap(__float_as_uint(ps), __float_as_uint(ps), false, false);
;       ps = __uint_as_float(rr[0]) + __uint_as_float(rr[1]); }
;     l_reg = l_reg * alpha + ps;
;     ...
;     PK4(p0, 0, pa0); PK4(p0, 8, pa1); PK4(p1, 0, pa2); PK4(p1, 8, pa3);
;     ...
; }
; __device__ __forceinline__ void qkt(f32x16& p0, f32x16& p1, const char* Ks, const bf16x8* qr, int r32, int hi, int comp) {
;     p0 = f32x16{}; p1 = f32x16{};
; #pragma unroll
;     for (int d0 = 0; d0 < 4; ++d0) { const int cb = (comp * 64 + d0 * 16 + hi * 8) * 2;
;         const bf16x8 b0 = *reinterpret_cast<const bf16x8*>(Ks + KSWZ(r32, cb));
;         const bf16x8 b1 = *reinterpret_cast<const bf16x8*>(Ks + KSWZ(32 + r32, cb));
;         p0 = __builtin_amdgcn_mfma_f32_32x32x16_bf16(b0, qr[d0], p0, 0, 0, 0);
;         p1 = __builtin_amdgcn_mfma_f32_32x32x16_bf16(b1, qr[d0], p1, 0, 0, 0); }
; }
; __device__ __forceinline__ int v_st(int k, int c) { const int kk = (k & ~0xC) | ((k & 4) << 1) | ((k & 8) >> 1); return ((kk >> 3) * 4 + (c >> 5)) * 512 + ((kk & 7) * 32 + (c & 31)) * 2; }
; __device__ __forceinline__ int v_rd_base(int lane) { return ((lane & 3) << 3) | (((lane >> 2) & 3) << 6) | (((lane >> 4) & 1) << 5) | (((lane >> 5) & 1) << 8); }
; template <int OFF> __device__ __forceinline__ s16x4 tr_read(int vb) {
;     s16x4 r; asm volatile("ds_read_b64_tr_b16 %0, %1 offset:%2" : "=&v"(r) : "v"(vb), "i"(OFF) : "memory"); return r;
; }
; template <int D0> __device__ __forceinline__ void pv_one(f32x16& od, int vb, bf16x8 pa0, bf16x8 pa1, bf16x8 pa2, bf16x8 pa3) {
;     const s16x4 l0 = tr_read<v_rd_off(D0, 0, 0)>(vb), h0 = tr_read<v_rd_off(D0, 0, 1)>(vb), l1 = tr_read<v_rd_off(D0, 1, 0)>(vb), h1 = tr_read<v_rd_off(D0, 1, 1)>(vb);
;     const s16x4 l2 = tr_read<v_rd_off(D0, 2, 0)>(vb), h2 = tr_read<v_rd_off(D0, 2, 1)>(vb), l3 = tr_read<v_rd_off(D0, 3, 0)>(vb), h3 = tr_read<v_rd_off(D0, 3, 1)>(vb);
;     asm volatile("s_waitcnt lgkmcnt(0)" ::: "memory"); SBAR();
.LBB0_266:
	v_fmamk_f32 v189, v64, 0x3e38aa3b, v179
	v_fmamk_f32 v211, v65, 0x3e38aa3b, v179
	v_fmamk_f32 v212, v66, 0x3e38aa3b, v179
	v_fmamk_f32 v213, v67, 0x3e38aa3b, v179
	v_fmamk_f32 v214, v68, 0x3e38aa3b, v179
	v_fmamk_f32 v182, v69, 0x3e38aa3b, v179
	v_fmamk_f32 v183, v70, 0x3e38aa3b, v179
	v_fmamk_f32 v184, v71, 0x3e38aa3b, v179
	v_fmamk_f32 v185, v72, 0x3e38aa3b, v179
	v_fmamk_f32 v186, v73, 0x3e38aa3b, v179
	v_fmamk_f32 v187, v74, 0x3e38aa3b, v179
	v_fmamk_f32 v188, v75, 0x3e38aa3b, v179
	v_fmamk_f32 v181, v76, 0x3e38aa3b, v179
	v_fmamk_f32 v215, v77, 0x3e38aa3b, v179
	v_fmamk_f32 v216, v78, 0x3e38aa3b, v179
	v_fmac_f32_e32 v179, 0x3e38aa3b, v79
	s_waitcnt lgkmcnt(0)
	s_barrier
	ds_read_b128 v[64:67], v170 offset:32768
	ds_read_b128 v[68:71], v170 offset:40960
	v_exp_f32_e32 v203, v181
	v_add_f32_e32 v181, 0, v127
	v_add_f32_e32 v181, v129, v181
	s_waitcnt lgkmcnt(1)
	v_mfma_f32_32x32x16_bf16 v[80:95], v[64:67], v[110:113], 0
	v_add_f32_e32 v181, v125, v181
	v_add_f32_e32 v181, v128, v181
	v_add_f32_e32 v181, v123, v181
	ds_read_b128 v[218:221], v171 offset:32768
	ds_read_b128 v[222:225], v171 offset:40960
	v_add_f32_e32 v181, v126, v181
	v_add_f32_e32 v181, v122, v181
	v_add_f32_e32 v181, v124, v181
	s_waitcnt lgkmcnt(2)
	v_mfma_f32_32x32x16_bf16 v[64:79], v[68:71], v[110:113], 0
	v_add_f32_e32 v181, v119, v181
	v_add_f32_e32 v181, v121, v181
	v_add_f32_e32 v181, v117, v181
	v_add_f32_e32 v181, v120, v181
	v_exp_f32_e32 v189, v189
	v_add_f32_e32 v181, v115, v181
	v_exp_f32_e32 v190, v211
	s_waitcnt lgkmcnt(1)
	v_mfma_f32_32x32x16_bf16 v[80:95], v[218:221], v[106:109], v[80:95]
	v_add_f32_e32 v181, v118, v181
	v_exp_f32_e32 v191, v212
	v_add_f32_e32 v181, v114, v181
	v_exp_f32_e32 v192, v213
	v_add_f32_e32 v181, v116, v181
	v_exp_f32_e32 v193, v214
	v_add_f32_e32 v181, v189, v181
	s_waitcnt lgkmcnt(0)
	v_mfma_f32_32x32x16_bf16 v[64:79], v[222:225], v[106:109], v[64:79]
	ds_read_b128 v[218:221], v173 offset:32768
	ds_read_b128 v[222:225], v173 offset:40960
	v_exp_f32_e32 v194, v182
	v_add_f32_e32 v181, v190, v181
	v_exp_f32_e32 v183, v183
	v_add_f32_e32 v181, v191, v181
	v_exp_f32_e32 v195, v184
	v_add_f32_e32 v181, v192, v181
	s_waitcnt lgkmcnt(1)
	v_mfma_f32_32x32x16_bf16 v[80:95], v[218:221], v[102:105], v[80:95]
	v_exp_f32_e32 v200, v185
	v_add_f32_e32 v181, v193, v181
	v_exp_f32_e32 v201, v186
	v_add_f32_e32 v181, v194, v181
	v_exp_f32_e32 v202, v187
	v_add_f32_e32 v181, v183, v181
	v_exp_f32_e32 v188, v188
	s_waitcnt lgkmcnt(0)
	v_mfma_f32_32x32x16_bf16 v[64:79], v[222:225], v[102:105], v[64:79]
	ds_read_b128 v[218:221], v172 offset:32768
	ds_read_b128 v[222:225], v172 offset:40960
	v_add_f32_e32 v181, v195, v181
	v_add_f32_e32 v181, v200, v181
	v_exp_f32_e32 v204, v215
	v_add_f32_e32 v181, v201, v181
	v_exp_f32_e32 v205, v216
	v_add_f32_e32 v181, v202, v181
	s_waitcnt lgkmcnt(1)
	v_mfma_f32_32x32x16_bf16 v[80:95], v[218:221], v[98:101], v[80:95]
	v_exp_f32_e32 v179, v179
	v_add_f32_e32 v181, v188, v181
	v_add_f32_e32 v181, v203, v181
	v_add_f32_e32 v181, v204, v181
	v_add_f32_e32 v181, v205, v181
	v_add_f32_e32 v181, v179, v181
	v_mov_b32_e32 v182, v181
	s_waitcnt lgkmcnt(0)
	v_mfma_f32_32x32x16_bf16 v[64:79], v[222:225], v[98:101], v[64:79]
	v_permlane32_swap_b32_e32 v181, v182
	v_cvt_pk_bf16_f32 v184, v127, v129
	v_cvt_pk_bf16_f32 v185, v125, v128
	v_cvt_pk_bf16_f32 v186, v123, v126
	v_cvt_pk_bf16_f32 v187, v122, v124
	v_cvt_pk_bf16_f32 v212, v119, v121
	v_cvt_pk_bf16_f32 v213, v117, v120
	v_cvt_pk_bf16_f32 v214, v115, v118
	v_cvt_pk_bf16_f32 v215, v114, v116
	v_cvt_pk_bf16_f32 v216, v189, v190
	v_cvt_pk_bf16_f32 v217, v191, v192
	v_cvt_pk_bf16_f32 v218, v193, v194
	v_cvt_pk_bf16_f32 v219, v183, v195
	v_cvt_pk_bf16_f32 v220, v200, v201
	v_cvt_pk_bf16_f32 v221, v202, v188
	v_cvt_pk_bf16_f32 v222, v203, v204
	v_cvt_pk_bf16_f32 v223, v205, v179
	s_nop 0
	v_permlane32_swap_b32_e32 v184, v186
	v_permlane32_swap_b32_e32 v185, v187
	v_permlane32_swap_b32_e32 v212, v214
	v_permlane32_swap_b32_e32 v213, v215
	v_permlane32_swap_b32_e32 v216, v218
	v_permlane32_swap_b32_e32 v217, v219
	v_permlane32_swap_b32_e32 v220, v222
	v_permlane32_swap_b32_e32 v221, v223
	v_add_u32_e32 v118, 0x20000, v176
	v_add_u32_e32 v122, 0x30000, v176
	global_load_dwordx4 v[114:117], v118, s[58:59]
	s_nop 0
	global_load_dwordx4 v[118:121], v118, s[28:29]
	s_nop 0
	global_load_dwordx4 v[126:129], v122, s[58:59]
	s_nop 0
	global_load_dwordx4 v[122:125], v122, s[28:29]
	ds_read_b64_tr_b16 v[224:225], v159 offset:0
	ds_read_b64_tr_b16 v[226:227], v159 offset:0x800
	ds_read_b64_tr_b16 v[228:229], v159 offset:0x1000
	ds_read_b64_tr_b16 v[230:231], v159 offset:0x1800
	ds_read_b64_tr_b16 v[232:233], v159 offset:0x2000
	ds_read_b64_tr_b16 v[234:235], v159 offset:0x2800
	ds_read_b64_tr_b16 v[236:237], v159 offset:0x3000
	ds_read_b64_tr_b16 v[238:239], v159 offset:0x3800
	s_waitcnt lgkmcnt(0)
	v_mfma_f32_32x32x16_bf16 v[48:63], v[184:187], v[224:227], v[48:63]
	ds_read_b64_tr_b16 v[224:225], v159 offset:0x200
	ds_read_b64_tr_b16 v[226:227], v159 offset:0xa00
	v_max_f32_e32 v255, v81, v81
	v_max_f32_e32 v210, v80, v80
	v_max_f32_e32 v255, v210, v255
	v_max3_f32 v255, v255, v82, v83
	v_max3_f32 v255, v255, v84, v85
	v_mfma_f32_32x32x16_bf16 v[48:63], v[212:215], v[228:231], v[48:63]
	ds_read_b64_tr_b16 v[228:229], v159 offset:0x1200
	ds_read_b64_tr_b16 v[230:231], v159 offset:0x1a00
	v_max3_f32 v255, v255, v86, v87
	v_max3_f32 v255, v255, v88, v89
	v_max3_f32 v255, v255, v90, v91
	v_max3_f32 v255, v255, v92, v93
	v_max3_f32 v255, v255, v94, v95
	v_mfma_f32_32x32x16_bf16 v[48:63], v[216:219], v[232:235], v[48:63]
	ds_read_b64_tr_b16 v[232:233], v159 offset:0x2200
	ds_read_b64_tr_b16 v[234:235], v159 offset:0x2a00
	v_max3_f32 v255, v255, v64, v65
	v_max3_f32 v255, v255, v66, v67
	v_max3_f32 v255, v255, v68, v69
	v_max3_f32 v255, v255, v70, v71
	v_max3_f32 v255, v255, v72, v73
	v_mfma_f32_32x32x16_bf16 v[48:63], v[220:223], v[236:239], v[48:63]
	ds_read_b64_tr_b16 v[236:237], v159 offset:0x3200
	ds_read_b64_tr_b16 v[238:239], v159 offset:0x3a00
	v_max3_f32 v255, v255, v74, v75
	v_max3_f32 v255, v255, v76, v77
	v_max3_f32 v255, v255, v78, v79
	v_mov_b32_e32 v210, v255
	s_nop 1
	v_permlane32_swap_b32_e32 v255, v210
	s_waitcnt lgkmcnt(0)
; __device__ __forceinline__ void partialSM(f32x16& p0, f32x16& p1, float& m_reg, float& mn, float& alpha) {
;     constexpr float C = SCALE * 1.4426950408889634f;
;     float pmax = p0[0];
; #pragma unroll
;     for (int r = 1; r < 16; ++r) pmax = fmaxf(pmax, p0[r]);
; #pragma unroll
;     for (int r = 0; r < 16; ++r) pmax = fmaxf(pmax, p1[r]);
;     { auto rr = __builtin_amdgcn_permlane32_swap(__float_as_uint(pmax), __float_as_uint(pmax), false, false);
;       pmax = fmaxf(__uint_as_float(rr[0]), __uint_as_float(rr[1])); }
;     if (__builtin_expect(__all(pmax - m_reg <= THR / SCALE), 1)) { mn = m_reg; alpha = 1.f; }
;     else { mn = fmaxf(m_reg, pmax); alpha = __builtin_amdgcn_exp2f((m_reg - mn) * C); m_reg = mn; }
;     const float mnC = -mn * C;
; #pragma unroll
;     for (int r = 0; r < 16; ++r) p0[r] = fmaf(p0[r], C, mnC);
; #pragma unroll
;     for (int r = 0; r < 16; ++r) p1[r] = fmaf(p1[r], C, mnC);
; #pragma unroll
;     for (int r = 0; r < 16; ++r) p0[r] = __builtin_amdgcn_exp2f(p0[r]);
; }
	v_mfma_f32_32x32x16_bf16 v[32:47], v[184:187], v[224:227], v[32:47]
	ds_read_b64_tr_b16 v[224:225], v159 offset:0x400
	ds_read_b64_tr_b16 v[226:227], v159 offset:0xc00
	v_max_f32_e32 v210, v210, v210
	v_max_f32_e32 v255, v255, v255
	v_max_f32_e32 v255, v255, v210
	v_sub_f32_e32 v210, v255, v175
	v_cmp_ge_f32_e32 vcc, s65, v210
	v_mfma_f32_32x32x16_bf16 v[32:47], v[212:215], v[228:231], v[32:47]
	ds_read_b64_tr_b16 v[228:229], v159 offset:0x1400
	ds_read_b64_tr_b16 v[230:231], v159 offset:0x1c00
	v_max_f32_e32 v210, v175, v175
	v_max_f32_e32 v210, v210, v255
	v_sub_f32_e32 v255, v175, v210
	v_mul_f32_e32 v255, 0x3e38aa3b, v255
	v_exp_f32_e32 v255, v255
	v_mfma_f32_32x32x16_bf16 v[32:47], v[216:219], v[232:235], v[32:47]
	ds_read_b64_tr_b16 v[232:233], v159 offset:0x2400
	ds_read_b64_tr_b16 v[234:235], v159 offset:0x2c00
	s_cmp_eq_u64 vcc, exec
	s_cselect_b64 s[8:9], -1, 0
	v_cndmask_b32_e64 v179, v255, 1.0, s[8:9]
	v_cndmask_b32_e64 v175, v210, v175, s[8:9]
	v_mul_f32_e32 v210, 0xbe38aa3b, v175
	v_mfma_f32_32x32x16_bf16 v[32:47], v[220:223], v[236:239], v[32:47]
	ds_read_b64_tr_b16 v[236:237], v159 offset:0x3400
	ds_read_b64_tr_b16 v[238:239], v159 offset:0x3c00
	v_pk_fma_f32 v[80:81], v[80:81], s[72:73], v[210:211] op_sel_hi:[1,0,0]
	v_pk_fma_f32 v[82:83], v[82:83], s[72:73], v[210:211] op_sel_hi:[1,0,0]
	v_pk_fma_f32 v[84:85], v[84:85], s[72:73], v[210:211] op_sel_hi:[1,0,0]
	v_pk_fma_f32 v[86:87], v[86:87], s[72:73], v[210:211] op_sel_hi:[1,0,0]
	v_pk_fma_f32 v[88:89], v[88:89], s[72:73], v[210:211] op_sel_hi:[1,0,0]
	s_waitcnt lgkmcnt(0)
	v_mfma_f32_32x32x16_bf16 v[16:31], v[184:187], v[224:227], v[16:31]
	ds_read_b64_tr_b16 v[224:225], v159 offset:0x600
	ds_read_b64_tr_b16 v[226:227], v159 offset:0xe00
	v_pk_fma_f32 v[90:91], v[90:91], s[72:73], v[210:211] op_sel_hi:[1,0,0]
	v_pk_fma_f32 v[92:93], v[92:93], s[72:73], v[210:211] op_sel_hi:[1,0,0]
	v_pk_fma_f32 v[94:95], v[94:95], s[72:73], v[210:211] op_sel_hi:[1,0,0]
	v_exp_f32_e32 v240, v80
	v_mfma_f32_32x32x16_bf16 v[16:31], v[212:215], v[228:231], v[16:31]
	ds_read_b64_tr_b16 v[228:229], v159 offset:0x1600
	ds_read_b64_tr_b16 v[230:231], v159 offset:0x1e00
	v_exp_f32_e32 v241, v81
	v_exp_f32_e32 v242, v82
	v_exp_f32_e32 v243, v83
	v_mfma_f32_32x32x16_bf16 v[16:31], v[216:219], v[232:235], v[16:31]
	ds_read_b64_tr_b16 v[232:233], v159 offset:0x2600
	ds_read_b64_tr_b16 v[234:235], v159 offset:0x2e00
	v_exp_f32_e32 v244, v84
	v_exp_f32_e32 v245, v85
	v_exp_f32_e32 v246, v86
	v_mfma_f32_32x32x16_bf16 v[16:31], v[220:223], v[236:239], v[16:31]
	ds_read_b64_tr_b16 v[236:237], v159 offset:0x3600
	ds_read_b64_tr_b16 v[238:239], v159 offset:0x3e00
	v_exp_f32_e32 v247, v87
	v_exp_f32_e32 v248, v88
	v_exp_f32_e32 v249, v89
	s_waitcnt lgkmcnt(0)
	v_mfma_f32_32x32x16_bf16 v[0:15], v[184:187], v[224:227], v[0:15]
	s_barrier
	s_waitcnt vmcnt(0)
	ds_write_b128 v163, v[114:117] offset:16384
	ds_write_b128 v164, v[126:129] offset:16384
	ds_write_b128 v161, v[118:121] offset:49152
	ds_write_b128 v162, v[122:125] offset:49152
	v_exp_f32_e32 v250, v90
	v_exp_f32_e32 v251, v91
	v_exp_f32_e32 v206, v92
	v_mfma_f32_32x32x16_bf16 v[0:15], v[212:215], v[228:231], v[0:15]
	v_exp_f32_e32 v207, v93
	v_exp_f32_e32 v208, v94
	v_exp_f32_e32 v209, v95
	v_mfma_f32_32x32x16_bf16 v[0:15], v[216:219], v[232:235], v[0:15]
	v_mfma_f32_32x32x16_bf16 v[0:15], v[220:223], v[236:239], v[0:15]
	s_cmp_lg_u64 s[8:9], 0
	s_cbranch_scc1 .LBB0_270
	s_and_saveexec_b64 s[2:3], s[6:7]
	ds_write_b32 v157, v179 offset:128
	s_or_b64 exec, exec, s[2:3]
	s_waitcnt lgkmcnt(0)
	ds_read_b128 v[114:117], v158 offset:224
	ds_read_b128 v[118:121], v158 offset:192
	ds_read_b128 v[122:125], v158 offset:160
	ds_read_b128 v[126:129], v158 offset:128
	s_waitcnt lgkmcnt(3)
	v_pk_mul_f32 v[62:63], v[62:63], v[116:117]
	s_waitcnt lgkmcnt(2)
	v_pk_mul_f32 v[58:59], v[58:59], v[120:121]
	s_waitcnt lgkmcnt(1)
	v_pk_mul_f32 v[54:55], v[54:55], v[124:125]
	s_waitcnt lgkmcnt(0)
	v_pk_mul_f32 v[50:51], v[50:51], v[128:129]
	v_pk_mul_f32 v[60:61], v[60:61], v[114:115]
	v_pk_mul_f32 v[56:57], v[56:57], v[118:119]
	v_pk_mul_f32 v[52:53], v[52:53], v[122:123]
	v_pk_mul_f32 v[48:49], v[48:49], v[126:127]
	v_pk_mul_f32 v[46:47], v[46:47], v[116:117]
	v_pk_mul_f32 v[42:43], v[42:43], v[120:121]
	v_pk_mul_f32 v[38:39], v[38:39], v[124:125]
	v_pk_mul_f32 v[34:35], v[34:35], v[128:129]
	v_pk_mul_f32 v[44:45], v[44:45], v[114:115]
	v_pk_mul_f32 v[40:41], v[40:41], v[118:119]
	v_pk_mul_f32 v[36:37], v[36:37], v[122:123]
	v_pk_mul_f32 v[32:33], v[32:33], v[126:127]
	v_pk_mul_f32 v[30:31], v[30:31], v[116:117]
	v_pk_mul_f32 v[26:27], v[26:27], v[120:121]
	v_pk_mul_f32 v[22:23], v[22:23], v[124:125]
	v_pk_mul_f32 v[18:19], v[18:19], v[128:129]
	v_pk_mul_f32 v[28:29], v[28:29], v[114:115]
	v_pk_mul_f32 v[24:25], v[24:25], v[118:119]
	v_pk_mul_f32 v[20:21], v[20:21], v[122:123]
	v_pk_mul_f32 v[16:17], v[16:17], v[126:127]
	v_pk_mul_f32 v[14:15], v[14:15], v[116:117]
	v_pk_mul_f32 v[10:11], v[10:11], v[120:121]
	v_pk_mul_f32 v[6:7], v[6:7], v[124:125]
	v_pk_mul_f32 v[2:3], v[2:3], v[128:129]
	v_pk_mul_f32 v[12:13], v[12:13], v[114:115]
	v_pk_mul_f32 v[8:9], v[8:9], v[118:119]
	v_pk_mul_f32 v[4:5], v[4:5], v[122:123]
	v_pk_mul_f32 v[0:1], v[0:1], v[126:127]
.LBB0_270:
	v_pk_fma_f32 v[128:129], v[64:65], s[72:73], v[210:211] op_sel_hi:[1,0,0]
	v_add_f32_e32 v64, v177, v178
	v_fmac_f32_e32 v64, v174, v169
	v_add_f32_e32 v169, v181, v182
	s_add_i32 s76, s76, 2
	v_pk_fma_f32 v[126:127], v[66:67], s[72:73], v[210:211] op_sel_hi:[1,0,0]
	v_pk_fma_f32 v[122:123], v[68:69], s[72:73], v[210:211] op_sel_hi:[1,0,0]
	v_pk_fma_f32 v[118:119], v[70:71], s[72:73], v[210:211] op_sel_hi:[1,0,0]
	v_pk_fma_f32 v[116:117], v[72:73], s[72:73], v[210:211] op_sel_hi:[1,0,0]
	v_pk_fma_f32 v[124:125], v[74:75], s[72:73], v[210:211] op_sel_hi:[1,0,0]
	v_pk_fma_f32 v[120:121], v[76:77], s[72:73], v[210:211] op_sel_hi:[1,0,0]
	v_pk_fma_f32 v[114:115], v[78:79], s[72:73], v[210:211] op_sel_hi:[1,0,0]
	v_fmac_f32_e32 v169, v64, v180
	s_cmp_ge_u32 s76, s67
	v_add_u32_e32 v176, 0x40000, v176
	v_mov_b32_e32 v174, v179
	s_waitcnt lgkmcnt(0)
	s_barrier
	s_cbranch_scc0 .LBB0_262

; __device__ __forceinline__ void finishSM(f32x16& p0, f32x16& p1, float alpha, float& l_reg, bf16x8& pa0, bf16x8& pa1, bf16x8& pa2, bf16x8& pa3) {
; #pragma unroll
;     for (int r = 0; r < 16; ++r) p1[r] = __builtin_amdgcn_exp2f(p1[r]);
;     float ps = 0;
; #pragma unroll
;     for (int r = 0; r < 16; ++r) ps += p0[r];
; #pragma unroll
;     for (int r = 0; r < 16; ++r) ps += p1[r];
;     { auto rr = __builtin_amdgcn_permlane32_swap(__float_as_uint(ps), __float_as_uint(ps), false, false);
;       ps = __uint_as_float(rr[0]) + __uint_as_float(rr[1]); }
;     l_reg = l_reg * alpha + ps;
;     ...
;     PK4(p0, 0, pa0); PK4(p0, 8, pa1); PK4(p1, 0, pa2); PK4(p1, 8, pa3);
;     ...
; }
; __device__ __forceinline__ void qkt(f32x16& p0, f32x16& p1, const char* Ks, const bf16x8* qr, int r32, int hi, int comp) {
;     p0 = f32x16{}; p1 = f32x16{};
; #pragma unroll
;     for (int d0 = 0; d0 < 4; ++d0) { const int cb = (comp * 64 + d0 * 16 + hi * 8) * 2;
;         const bf16x8 b0 = *reinterpret_cast<const bf16x8*>(Ks + KSWZ(r32, cb));
;         const bf16x8 b1 = *reinterpret_cast<const bf16x8*>(Ks + KSWZ(32 + r32, cb));
;         p0 = __builtin_amdgcn_mfma_f32_32x32x16_bf16(b0, qr[d0], p0, 0, 0, 0);
;         p1 = __builtin_amdgcn_mfma_f32_32x32x16_bf16(b1, qr[d0], p1, 0, 0, 0); }
; }
; __device__ __forceinline__ int v_st(int k, int c) { const int kk = (k & ~0xC) | ((k & 4) << 1) | ((k & 8) >> 1); return ((kk >> 3) * 4 + (c >> 5)) * 512 + ((kk & 7) * 32 + (c & 31)) * 2; }
; __device__ __forceinline__ int v_rd_base(int lane) { return ((lane & 3) << 3) | (((lane >> 2) & 3) << 6) | (((lane >> 4) & 1) << 5) | (((lane >> 5) & 1) << 8); }
; template <int OFF> __device__ __forceinline__ s16x4 tr_read(int vb) {
;     s16x4 r; asm volatile("ds_read_b64_tr_b16 %0, %1 offset:%2" : "=&v"(r) : "v"(vb), "i"(OFF) : "memory"); return r;
; }
; template <int D0> __device__ __forceinline__ void pv_one(f32x16& od, int vb, bf16x8 pa0, bf16x8 pa1, bf16x8 pa2, bf16x8 pa3) {
;     const s16x4 l0 = tr_read<v_rd_off(D0, 0, 0)>(vb), h0 = tr_read<v_rd_off(D0, 0, 1)>(vb), l1 = tr_read<v_rd_off(D0, 1, 0)>(vb), h1 = tr_read<v_rd_off(D0, 1, 1)>(vb);
;     const s16x4 l2 = tr_read<v_rd_off(D0, 2, 0)>(vb), h2 = tr_read<v_rd_off(D0, 2, 1)>(vb), l3 = tr_read<v_rd_off(D0, 3, 0)>(vb), h3 = tr_read<v_rd_off(D0, 3, 1)>(vb);
;     asm volatile("s_waitcnt lgkmcnt(0)" ::: "memory"); SBAR();
.LBB0_284:
	v_fmamk_f32 v167, v64, 0x3e38aa3b, v137
	v_fmamk_f32 v168, v65, 0x3e38aa3b, v137
	v_fmamk_f32 v169, v66, 0x3e38aa3b, v137
	v_fmamk_f32 v170, v67, 0x3e38aa3b, v137
	v_fmamk_f32 v171, v68, 0x3e38aa3b, v137
	v_fmamk_f32 v144, v69, 0x3e38aa3b, v137
	v_fmamk_f32 v145, v70, 0x3e38aa3b, v137
	v_fmamk_f32 v146, v71, 0x3e38aa3b, v137
	v_fmamk_f32 v147, v72, 0x3e38aa3b, v137
	v_fmamk_f32 v148, v73, 0x3e38aa3b, v137
	v_fmamk_f32 v149, v74, 0x3e38aa3b, v137
	v_fmamk_f32 v166, v75, 0x3e38aa3b, v137
	v_fmamk_f32 v139, v76, 0x3e38aa3b, v137
	v_fmamk_f32 v172, v77, 0x3e38aa3b, v137
	v_fmamk_f32 v173, v78, 0x3e38aa3b, v137
	v_fmac_f32_e32 v137, 0x3e38aa3b, v79
	s_waitcnt lgkmcnt(0)
	s_barrier
	ds_read_b128 v[64:67], v140 offset:32768
	ds_read_b128 v[68:71], v140 offset:40960
	ds_read_b128 v[174:177], v143 offset:32768
	ds_read_b128 v[178:181], v143 offset:40960
	v_exp_f32_e32 v185, v139
	v_add_f32_e32 v139, 0, v127
	s_waitcnt lgkmcnt(3)
	v_mfma_f32_32x32x16_bf16 v[80:95], v[64:67], v[110:113], 0
	v_add_f32_e32 v139, v129, v139
	v_add_f32_e32 v139, v125, v139
	v_add_f32_e32 v139, v128, v139
	v_add_f32_e32 v139, v123, v139
	v_add_f32_e32 v139, v126, v139
	v_add_f32_e32 v139, v122, v139
	v_add_f32_e32 v139, v124, v139
	s_waitcnt lgkmcnt(2)
	v_mfma_f32_32x32x16_bf16 v[64:79], v[68:71], v[110:113], 0
	v_add_f32_e32 v139, v119, v139
	v_add_f32_e32 v139, v121, v139
	v_add_f32_e32 v139, v117, v139
	v_add_f32_e32 v139, v120, v139
	v_add_f32_e32 v139, v115, v139
	v_add_f32_e32 v139, v118, v139
	v_add_f32_e32 v139, v114, v139
	s_waitcnt lgkmcnt(1)
	v_mfma_f32_32x32x16_bf16 v[80:95], v[174:177], v[106:109], v[80:95]
	v_add_f32_e32 v139, v116, v139
	v_exp_f32_e32 v145, v145
	v_exp_f32_e32 v182, v148
	v_exp_f32_e32 v183, v149
	v_exp_f32_e32 v184, v166
	v_exp_f32_e32 v186, v172
	v_exp_f32_e32 v187, v173
	s_waitcnt lgkmcnt(0)
	v_mfma_f32_32x32x16_bf16 v[64:79], v[178:181], v[106:109], v[64:79]
	ds_read_b128 v[174:177], v142 offset:32768
	ds_read_b128 v[178:181], v142 offset:40960
	v_exp_f32_e32 v137, v137
	s_waitcnt lgkmcnt(1)
	v_mfma_f32_32x32x16_bf16 v[80:95], v[174:177], v[102:105], v[80:95]
	s_waitcnt lgkmcnt(0)
	v_mfma_f32_32x32x16_bf16 v[64:79], v[178:181], v[102:105], v[64:79]
	ds_read_b128 v[174:177], v141 offset:32768
	ds_read_b128 v[178:181], v141 offset:40960
	s_waitcnt lgkmcnt(1)
	v_mfma_f32_32x32x16_bf16 v[80:95], v[174:177], v[98:101], v[80:95]
	v_exp_f32_e32 v174, v167
	v_exp_f32_e32 v175, v168
	v_exp_f32_e32 v176, v169
	v_exp_f32_e32 v177, v170
	v_add_f32_e32 v139, v174, v139
	v_add_f32_e32 v139, v175, v139
	v_add_f32_e32 v139, v176, v139
	s_waitcnt lgkmcnt(0)
	v_mfma_f32_32x32x16_bf16 v[64:79], v[178:181], v[98:101], v[64:79]
	v_exp_f32_e32 v178, v171
	v_exp_f32_e32 v179, v144
	v_exp_f32_e32 v180, v146
	v_add_f32_e32 v139, v177, v139
	v_exp_f32_e32 v181, v147
	v_add_f32_e32 v139, v178, v139
	v_add_f32_e32 v139, v179, v139
	v_add_f32_e32 v139, v145, v139
	v_add_f32_e32 v139, v180, v139
	v_add_f32_e32 v139, v181, v139
	v_add_f32_e32 v139, v182, v139
	v_add_f32_e32 v139, v183, v139
	v_add_f32_e32 v139, v184, v139
	v_add_f32_e32 v139, v185, v139
	v_add_f32_e32 v139, v186, v139
	v_add_f32_e32 v139, v187, v139
	v_add_f32_e32 v139, v137, v139
	v_mov_b32_e32 v144, v139
	s_nop 1
	v_permlane32_swap_b32_e32 v139, v144
	v_cvt_pk_bf16_f32 v146, v127, v129
	v_cvt_pk_bf16_f32 v147, v125, v128
	v_cvt_pk_bf16_f32 v148, v123, v126
	v_cvt_pk_bf16_f32 v149, v122, v124
	v_cvt_pk_bf16_f32 v166, v119, v121
	v_cvt_pk_bf16_f32 v167, v117, v120
	v_cvt_pk_bf16_f32 v168, v115, v118
	v_cvt_pk_bf16_f32 v169, v114, v116
	v_cvt_pk_bf16_f32 v170, v174, v175
	v_cvt_pk_bf16_f32 v171, v176, v177
	v_cvt_pk_bf16_f32 v172, v178, v179
	v_cvt_pk_bf16_f32 v173, v145, v180
	v_cvt_pk_bf16_f32 v174, v181, v182
	v_cvt_pk_bf16_f32 v175, v183, v184
	v_cvt_pk_bf16_f32 v176, v185, v186
	v_cvt_pk_bf16_f32 v177, v187, v137
	s_nop 0
	v_permlane32_swap_b32_e32 v146, v148
	v_permlane32_swap_b32_e32 v147, v149
	v_permlane32_swap_b32_e32 v166, v168
	v_permlane32_swap_b32_e32 v167, v169
	v_permlane32_swap_b32_e32 v170, v172
	v_permlane32_swap_b32_e32 v171, v173
	v_permlane32_swap_b32_e32 v174, v176
	v_permlane32_swap_b32_e32 v175, v177
	v_add_u32_e32 v118, 0x20000, v96
	v_add_u32_e32 v122, 0x30000, v96
	global_load_dwordx4 v[114:117], v118, s[58:59]
	s_nop 0
	global_load_dwordx4 v[118:121], v118, s[28:29]
	s_nop 0
	global_load_dwordx4 v[126:129], v122, s[58:59]
	s_nop 0
	global_load_dwordx4 v[122:125], v122, s[28:29]
	ds_read_b64_tr_b16 v[178:179], v159 offset:0
	ds_read_b64_tr_b16 v[180:181], v159 offset:0x800
	ds_read_b64_tr_b16 v[182:183], v159 offset:0x1000
	ds_read_b64_tr_b16 v[184:185], v159 offset:0x1800
	ds_read_b64_tr_b16 v[186:187], v159 offset:0x2000
	ds_read_b64_tr_b16 v[188:189], v159 offset:0x2800
	ds_read_b64_tr_b16 v[212:213], v159 offset:0x3000
	ds_read_b64_tr_b16 v[214:215], v159 offset:0x3800
	s_waitcnt lgkmcnt(0)
	v_mfma_f32_32x32x16_bf16 v[48:63], v[146:149], v[178:181], v[48:63]
	ds_read_b64_tr_b16 v[178:179], v159 offset:0x200
	ds_read_b64_tr_b16 v[180:181], v159 offset:0xa00
	v_max_f32_e32 v255, v81, v81
	v_max_f32_e32 v210, v80, v80
	v_max_f32_e32 v255, v210, v255
	v_max3_f32 v255, v255, v82, v83
	v_max3_f32 v255, v255, v84, v85
	v_mfma_f32_32x32x16_bf16 v[48:63], v[166:169], v[182:185], v[48:63]
	ds_read_b64_tr_b16 v[182:183], v159 offset:0x1200
	ds_read_b64_tr_b16 v[184:185], v159 offset:0x1a00
	v_max3_f32 v255, v255, v86, v87
	v_max3_f32 v255, v255, v88, v89
	v_max3_f32 v255, v255, v90, v91
	v_max3_f32 v255, v255, v92, v93
	v_max3_f32 v255, v255, v94, v95
	v_mfma_f32_32x32x16_bf16 v[48:63], v[170:173], v[186:189], v[48:63]
	ds_read_b64_tr_b16 v[186:187], v159 offset:0x2200
	ds_read_b64_tr_b16 v[188:189], v159 offset:0x2a00
	v_max3_f32 v255, v255, v64, v65
	v_max3_f32 v255, v255, v66, v67
	v_max3_f32 v255, v255, v68, v69
	v_max3_f32 v255, v255, v70, v71
	v_max3_f32 v255, v255, v72, v73
	v_mfma_f32_32x32x16_bf16 v[48:63], v[174:177], v[212:215], v[48:63]
	ds_read_b64_tr_b16 v[212:213], v159 offset:0x3200
	ds_read_b64_tr_b16 v[214:215], v159 offset:0x3a00
	v_max3_f32 v255, v255, v74, v75
	v_max3_f32 v255, v255, v76, v77
	v_max3_f32 v255, v255, v78, v79
	v_mov_b32_e32 v210, v255
	s_nop 1
	v_permlane32_swap_b32_e32 v255, v210
	s_waitcnt lgkmcnt(0)
; __device__ __forceinline__ void partialSM(f32x16& p0, f32x16& p1, float& m_reg, float& mn, float& alpha) {
;     constexpr float C = SCALE * 1.4426950408889634f;
;     float pmax = p0[0];
; #pragma unroll
;     for (int r = 1; r < 16; ++r) pmax = fmaxf(pmax, p0[r]);
; #pragma unroll
;     for (int r = 0; r < 16; ++r) pmax = fmaxf(pmax, p1[r]);
;     { auto rr = __builtin_amdgcn_permlane32_swap(__float_as_uint(pmax), __float_as_uint(pmax), false, false);
;       pmax = fmaxf(__uint_as_float(rr[0]), __uint_as_float(rr[1])); }
;     if (__builtin_expect(__all(pmax - m_reg <= THR / SCALE), 1)) { mn = m_reg; alpha = 1.f; }
;     else { mn = fmaxf(m_reg, pmax); alpha = __builtin_amdgcn_exp2f((m_reg - mn) * C); m_reg = mn; }
;     const float mnC = -mn * C;
; #pragma unroll
;     for (int r = 0; r < 16; ++r) p0[r] = fmaf(p0[r], C, mnC);
; #pragma unroll
;     for (int r = 0; r < 16; ++r) p1[r] = fmaf(p1[r], C, mnC);
; #pragma unroll
;     for (int r = 0; r < 16; ++r) p0[r] = __builtin_amdgcn_exp2f(p0[r]);
; }
	v_mfma_f32_32x32x16_bf16 v[32:47], v[146:149], v[178:181], v[32:47]
	ds_read_b64_tr_b16 v[178:179], v159 offset:0x400
	ds_read_b64_tr_b16 v[180:181], v159 offset:0xc00
	v_max_f32_e32 v210, v210, v210
	v_max_f32_e32 v255, v255, v255
	v_max_f32_e32 v255, v255, v210
	v_sub_f32_e32 v210, v255, v134
	v_cmp_ge_f32_e32 vcc, s65, v210
	v_mfma_f32_32x32x16_bf16 v[32:47], v[166:169], v[182:185], v[32:47]
	ds_read_b64_tr_b16 v[182:183], v159 offset:0x1400
	ds_read_b64_tr_b16 v[184:185], v159 offset:0x1c00
	v_max_f32_e32 v210, v134, v134
	v_max_f32_e32 v210, v210, v255
	v_sub_f32_e32 v255, v134, v210
	v_mul_f32_e32 v255, 0x3e38aa3b, v255
	v_exp_f32_e32 v255, v255
	v_mfma_f32_32x32x16_bf16 v[32:47], v[170:173], v[186:189], v[32:47]
	ds_read_b64_tr_b16 v[186:187], v159 offset:0x2400
	ds_read_b64_tr_b16 v[188:189], v159 offset:0x2c00
	s_cmp_eq_u64 vcc, exec
	s_cselect_b64 s[8:9], -1, 0
	v_cndmask_b32_e64 v137, v255, 1.0, s[8:9]
	v_cndmask_b32_e64 v134, v210, v134, s[8:9]
	v_mul_f32_e32 v210, 0xbe38aa3b, v134
	v_mfma_f32_32x32x16_bf16 v[32:47], v[174:177], v[212:215], v[32:47]
	ds_read_b64_tr_b16 v[212:213], v159 offset:0x3400
	ds_read_b64_tr_b16 v[214:215], v159 offset:0x3c00
	v_pk_fma_f32 v[80:81], v[80:81], s[72:73], v[210:211] op_sel_hi:[1,0,0]
	v_pk_fma_f32 v[82:83], v[82:83], s[72:73], v[210:211] op_sel_hi:[1,0,0]
	v_pk_fma_f32 v[84:85], v[84:85], s[72:73], v[210:211] op_sel_hi:[1,0,0]
	v_pk_fma_f32 v[86:87], v[86:87], s[72:73], v[210:211] op_sel_hi:[1,0,0]
	v_pk_fma_f32 v[88:89], v[88:89], s[72:73], v[210:211] op_sel_hi:[1,0,0]
	s_waitcnt lgkmcnt(0)
	v_mfma_f32_32x32x16_bf16 v[16:31], v[146:149], v[178:181], v[16:31]
	ds_read_b64_tr_b16 v[178:179], v159 offset:0x600
	ds_read_b64_tr_b16 v[180:181], v159 offset:0xe00
	v_pk_fma_f32 v[90:91], v[90:91], s[72:73], v[210:211] op_sel_hi:[1,0,0]
	v_pk_fma_f32 v[92:93], v[92:93], s[72:73], v[210:211] op_sel_hi:[1,0,0]
	v_pk_fma_f32 v[94:95], v[94:95], s[72:73], v[210:211] op_sel_hi:[1,0,0]
	v_exp_f32_e32 v240, v80
	v_mfma_f32_32x32x16_bf16 v[16:31], v[166:169], v[182:185], v[16:31]
	ds_read_b64_tr_b16 v[182:183], v159 offset:0x1600
	ds_read_b64_tr_b16 v[184:185], v159 offset:0x1e00
	v_exp_f32_e32 v241, v81
	v_exp_f32_e32 v242, v82
	v_exp_f32_e32 v243, v83
	v_mfma_f32_32x32x16_bf16 v[16:31], v[170:173], v[186:189], v[16:31]
	ds_read_b64_tr_b16 v[186:187], v159 offset:0x2600
	ds_read_b64_tr_b16 v[188:189], v159 offset:0x2e00
	v_exp_f32_e32 v244, v84
	v_exp_f32_e32 v245, v85
	v_exp_f32_e32 v246, v86
	v_mfma_f32_32x32x16_bf16 v[16:31], v[174:177], v[212:215], v[16:31]
	ds_read_b64_tr_b16 v[212:213], v159 offset:0x3600
	ds_read_b64_tr_b16 v[214:215], v159 offset:0x3e00
	v_exp_f32_e32 v247, v87
	v_exp_f32_e32 v248, v88
	v_exp_f32_e32 v249, v89
	s_waitcnt lgkmcnt(0)
	v_mfma_f32_32x32x16_bf16 v[0:15], v[146:149], v[178:181], v[0:15]
	s_barrier
	s_waitcnt vmcnt(0)
	ds_write_b128 v163, v[114:117] offset:16384
	ds_write_b128 v164, v[126:129] offset:16384
	ds_write_b128 v161, v[118:121] offset:49152
	ds_write_b128 v162, v[122:125] offset:49152
	v_exp_f32_e32 v250, v90
	v_exp_f32_e32 v251, v91
	v_exp_f32_e32 v206, v92
	v_mfma_f32_32x32x16_bf16 v[0:15], v[166:169], v[182:185], v[0:15]
	v_exp_f32_e32 v207, v93
	v_exp_f32_e32 v208, v94
	v_exp_f32_e32 v209, v95
	v_mfma_f32_32x32x16_bf16 v[0:15], v[170:173], v[186:189], v[0:15]
	v_mfma_f32_32x32x16_bf16 v[0:15], v[174:177], v[212:215], v[0:15]
	s_cmp_lg_u64 s[8:9], 0
	s_cbranch_scc1 .LBB0_288
	s_and_saveexec_b64 s[2:3], s[6:7]
	ds_write_b32 v157, v137 offset:128
	s_or_b64 exec, exec, s[2:3]
	s_waitcnt lgkmcnt(0)
	ds_read_b128 v[114:117], v158 offset:224
	ds_read_b128 v[118:121], v158 offset:192
	ds_read_b128 v[122:125], v158 offset:160
	ds_read_b128 v[126:129], v158 offset:128
	s_waitcnt lgkmcnt(3)
	v_pk_mul_f32 v[62:63], v[62:63], v[116:117]
	s_waitcnt lgkmcnt(2)
	v_pk_mul_f32 v[58:59], v[58:59], v[120:121]
	s_waitcnt lgkmcnt(1)
	v_pk_mul_f32 v[54:55], v[54:55], v[124:125]
	s_waitcnt lgkmcnt(0)
	v_pk_mul_f32 v[50:51], v[50:51], v[128:129]
	v_pk_mul_f32 v[60:61], v[60:61], v[114:115]
	v_pk_mul_f32 v[56:57], v[56:57], v[118:119]
	v_pk_mul_f32 v[52:53], v[52:53], v[122:123]
	v_pk_mul_f32 v[48:49], v[48:49], v[126:127]
	v_pk_mul_f32 v[46:47], v[46:47], v[116:117]
	v_pk_mul_f32 v[42:43], v[42:43], v[120:121]
	v_pk_mul_f32 v[38:39], v[38:39], v[124:125]
	v_pk_mul_f32 v[34:35], v[34:35], v[128:129]
	v_pk_mul_f32 v[44:45], v[44:45], v[114:115]
	v_pk_mul_f32 v[40:41], v[40:41], v[118:119]
	v_pk_mul_f32 v[36:37], v[36:37], v[122:123]
	v_pk_mul_f32 v[32:33], v[32:33], v[126:127]
	v_pk_mul_f32 v[30:31], v[30:31], v[116:117]
	v_pk_mul_f32 v[26:27], v[26:27], v[120:121]
	v_pk_mul_f32 v[22:23], v[22:23], v[124:125]
	v_pk_mul_f32 v[18:19], v[18:19], v[128:129]
	v_pk_mul_f32 v[28:29], v[28:29], v[114:115]
	v_pk_mul_f32 v[24:25], v[24:25], v[118:119]
	v_pk_mul_f32 v[20:21], v[20:21], v[122:123]
	v_pk_mul_f32 v[16:17], v[16:17], v[126:127]
	v_pk_mul_f32 v[14:15], v[14:15], v[116:117]
	v_pk_mul_f32 v[10:11], v[10:11], v[120:121]
	v_pk_mul_f32 v[6:7], v[6:7], v[124:125]
	v_pk_mul_f32 v[2:3], v[2:3], v[128:129]
	v_pk_mul_f32 v[12:13], v[12:13], v[114:115]
	v_pk_mul_f32 v[8:9], v[8:9], v[118:119]
	v_pk_mul_f32 v[4:5], v[4:5], v[122:123]
	v_pk_mul_f32 v[0:1], v[0:1], v[126:127]
.LBB0_288:
	v_pk_fma_f32 v[128:129], v[64:65], s[72:73], v[210:211] op_sel_hi:[1,0,0]
	v_add_f32_e32 v64, v135, v136
	v_fmac_f32_e32 v64, v133, v132
	v_add_f32_e32 v132, v139, v144
	s_add_i32 s36, s36, 2
	v_pk_fma_f32 v[126:127], v[66:67], s[72:73], v[210:211] op_sel_hi:[1,0,0]
	v_pk_fma_f32 v[122:123], v[68:69], s[72:73], v[210:211] op_sel_hi:[1,0,0]
	v_pk_fma_f32 v[118:119], v[70:71], s[72:73], v[210:211] op_sel_hi:[1,0,0]
	v_pk_fma_f32 v[116:117], v[72:73], s[72:73], v[210:211] op_sel_hi:[1,0,0]
	v_pk_fma_f32 v[124:125], v[74:75], s[72:73], v[210:211] op_sel_hi:[1,0,0]
	v_pk_fma_f32 v[120:121], v[76:77], s[72:73], v[210:211] op_sel_hi:[1,0,0]
	v_pk_fma_f32 v[114:115], v[78:79], s[72:73], v[210:211] op_sel_hi:[1,0,0]
	v_fmac_f32_e32 v132, v64, v138
	s_cmp_lt_u32 s36, s67
	v_add_u32_e32 v96, 0x40000, v96
	v_mov_b32_e32 v133, v137
	s_waitcnt lgkmcnt(0)
	s_barrier
	s_cbranch_scc1 .LBB0_280

; #define PG8_STAGE(bufoff, gbase, voff) do { _Pragma("unroll") for (int _i = 0; _i < 2; ++_i) \
;         __builtin_amdgcn_global_load_lds((const unsigned*)((const char*)(gbase) + (voff)[_i]), (LAS unsigned*)(lds + (bufoff) + ldsw + _i * 8192), 16, 0, 0); } while (0)
; #define PG8_LDA(dst, b, h) do { _Pragma("unroll") for (int m = 0; m < 4; ++m) _Pragma("unroll") for (int k = 0; k < 2; ++k) dst[m][k] = *(const LAS bf16x8*)(lds + PG8_SA(b, h) + aoff + m * 2048 + k * 1024); } while (0)
; #define PG8_LDB(dst, b, h) do { _Pragma("unroll") for (int n = 0; n < 2; ++n) _Pragma("unroll") for (int k = 0; k < 2; ++k) dst[n][k] = *(const LAS bf16x8*)(lds + PG8_SB(b, h) + boff + n * 2048 + k * 1024); } while (0)
; #define PG8_MMA(ai, bj, At, Bt) do { __builtin_amdgcn_s_setprio(1); _Pragma("unroll") for (int m = 0; m < 4; ++m) _Pragma("unroll") for (int n = 0; n < 2; ++n) _Pragma("unroll") for (int k = 0; k < 2; ++k) \
;         acc[ai][bj][m][n] = __builtin_amdgcn_mfma_f32_16x16x32_bf16(Bt[n][k], At[m][k], acc[ai][bj][m][n], 0, 0, 0); __builtin_amdgcn_s_setprio(0); } while (0)
; #define PG8_WAIT_V(n) asm volatile("s_waitcnt vmcnt(" #n ")" ::: "memory")
; #define PG8_WAIT_L(n) asm volatile("s_waitcnt lgkmcnt(" #n ")" ::: "memory")
; #define PG8_BAR __builtin_amdgcn_s_barrier()
; #define PG8_SCHED __builtin_amdgcn_sched_barrier(0)
; template <class Epi>
; __device__ __forceinline__ void gemm_phase(LAS unsigned char* lds, const Gemm g, const Epi& E) {
;     ...
;         for (int t = 0; t < nt; t += 2) {
;             const bool last = (t == nt - 2);
;             const char* a1 = cA + (size_t)(t + 1) * kstep;
;             const char* a2 = last ? nA : cA + (size_t)(t + 2) * kstep; const char* b2 = last ? nB : cB + (size_t)(t + 2) * kstep;
;             const char* a3 = a2 + kstep; const char* b3 = b2 + kstep;
;             PG8_LDB(B0, 0, 0); PG8_LDB(B1, 0, 1); PG8_SCHED; PG8_LDA(At, 0, 0); PG8_STAGE(PG8_SA(1, 1), a1 + hstepA, voffA);
;             PG8_WAIT_V(8); PG8_WAIT_L(0); PG8_BAR; PG8_MMA(0, 0, At, B0); PG8_MMA(0, 1, At, B1); PG8_BAR; PG8_SCHED;
;             PG8_LDA(At, 0, 1); PG8_STAGE(PG8_SB(0, 0), b2, voffB); PG8_STAGE(PG8_SB(0, 1), b2 + hstepB, voffB); PG8_STAGE(PG8_SA(0, 0), a2, voffA);
;             PG8_WAIT_V(8); PG8_WAIT_L(0); PG8_BAR; PG8_MMA(1, 0, At, B0); PG8_MMA(1, 1, At, B1); PG8_BAR; PG8_SCHED;
.LBB0_324:
	s_add_i32 s18, s14, 2
	s_add_u32 s19, s2, 0x80
	s_addc_u32 s15, s3, 0
	s_add_i32 s22, 0, 0x10000
	s_cmp_eq_u32 s44, s14
	s_cselect_b32 s15, s49, s15
	s_cselect_b32 s14, s48, s19
	v_add_u32_e32 v96, s22, v213
	s_cselect_b32 s21, s59, s17
	s_cselect_b32 s20, s58, s16
	s_add_i32 s19, 0, 0x14000
	ds_read_b128 v[130:133], v96
	ds_read_b128 v[134:137], v96 offset:1024
	ds_read_b128 v[138:141], v96 offset:2048
	ds_read_b128 v[142:145], v96 offset:3072
	v_add_u32_e32 v96, s19, v213
	ds_read_b128 v[146:149], v96
	ds_read_b128 v[150:153], v96 offset:1024
	ds_read_b128 v[166:169], v96 offset:2048
	ds_read_b128 v[170:173], v96 offset:3072
	v_lshl_add_u64 v[190:191], s[2:3], 0, v[162:163]
	s_add_i32 m0, s8, 0xc000
	ds_read_b128 v[174:177], v216
	ds_read_b128 v[178:181], v216 offset:1024
	ds_read_b128 v[182:185], v216 offset:2048
	ds_read_b128 v[186:189], v216 offset:3072
	ds_read_b128 v[218:221], v216 offset:4096
	ds_read_b128 v[222:225], v216 offset:5120
	ds_read_b128 v[226:229], v216 offset:6144
	ds_read_b128 v[230:233], v216 offset:7168
	global_load_lds_dwordx4 v[190:191], off
	v_lshl_add_u64 v[190:191], s[2:3], 0, v[164:165]
	s_add_i32 m0, s8, 0xe000
	s_nop 0
	global_load_lds_dwordx4 v[190:191], off
	s_waitcnt vmcnt(8)
	s_waitcnt lgkmcnt(0)
	s_barrier
	s_setprio 1
	v_mfma_f32_16x16x32_bf16 v[126:129], v[130:133], v[174:177], v[126:129]
	v_mfma_f32_16x16x32_bf16 v[122:125], v[138:141], v[174:177], v[122:125]
	v_mfma_f32_16x16x32_bf16 v[110:113], v[130:133], v[182:185], v[110:113]
	v_mfma_f32_16x16x32_bf16 v[106:109], v[138:141], v[182:185], v[106:109]
	v_mfma_f32_16x16x32_bf16 v[92:95], v[130:133], v[218:221], v[92:95]
	v_mfma_f32_16x16x32_bf16 v[88:91], v[138:141], v[218:221], v[88:91]
	v_mfma_f32_16x16x32_bf16 v[76:79], v[130:133], v[226:229], v[76:79]
	v_mfma_f32_16x16x32_bf16 v[72:75], v[138:141], v[226:229], v[72:75]
	v_mfma_f32_16x16x32_bf16 v[126:129], v[134:137], v[178:181], v[126:129]
	v_mfma_f32_16x16x32_bf16 v[122:125], v[142:145], v[178:181], v[122:125]
	v_mfma_f32_16x16x32_bf16 v[110:113], v[134:137], v[186:189], v[110:113]
	v_mfma_f32_16x16x32_bf16 v[106:109], v[142:145], v[186:189], v[106:109]
	v_mfma_f32_16x16x32_bf16 v[92:95], v[134:137], v[222:225], v[92:95]
	v_mfma_f32_16x16x32_bf16 v[88:91], v[142:145], v[222:225], v[88:91]
	v_mfma_f32_16x16x32_bf16 v[76:79], v[134:137], v[230:233], v[76:79]
	v_mfma_f32_16x16x32_bf16 v[72:75], v[142:145], v[230:233], v[72:75]
	s_setprio 0
	s_setprio 1
	v_mfma_f32_16x16x32_bf16 v[118:121], v[146:149], v[174:177], v[118:121]
	v_mfma_f32_16x16x32_bf16 v[114:117], v[166:169], v[174:177], v[114:117]
	v_mfma_f32_16x16x32_bf16 v[102:105], v[146:149], v[182:185], v[102:105]
	v_mfma_f32_16x16x32_bf16 v[98:101], v[166:169], v[182:185], v[98:101]
	v_mfma_f32_16x16x32_bf16 v[84:87], v[146:149], v[218:221], v[84:87]
	v_mfma_f32_16x16x32_bf16 v[80:83], v[166:169], v[218:221], v[80:83]
	v_mfma_f32_16x16x32_bf16 v[68:71], v[146:149], v[226:229], v[68:71]
	v_mfma_f32_16x16x32_bf16 v[64:67], v[166:169], v[226:229], v[64:67]
	v_mfma_f32_16x16x32_bf16 v[118:121], v[150:153], v[178:181], v[118:121]
	v_mfma_f32_16x16x32_bf16 v[114:117], v[170:173], v[178:181], v[114:117]
	v_mfma_f32_16x16x32_bf16 v[102:105], v[150:153], v[186:189], v[102:105]
	v_mfma_f32_16x16x32_bf16 v[98:101], v[170:173], v[186:189], v[98:101]
	v_mfma_f32_16x16x32_bf16 v[84:87], v[150:153], v[222:225], v[84:87]
	v_mfma_f32_16x16x32_bf16 v[80:83], v[170:173], v[222:225], v[80:83]
	v_mfma_f32_16x16x32_bf16 v[68:71], v[150:153], v[230:233], v[68:71]
	v_mfma_f32_16x16x32_bf16 v[64:67], v[170:173], v[230:233], v[64:67]
	s_setprio 0
	s_barrier
	s_add_i32 s22, s22, s45
	v_lshl_add_u64 v[190:191], s[20:21], 0, v[156:157]
	s_mov_b32 m0, s22
	ds_read_b128 v[174:177], v216 offset:16384
	ds_read_b128 v[178:181], v216 offset:17408
	ds_read_b128 v[182:185], v216 offset:18432
	ds_read_b128 v[186:189], v216 offset:19456
	ds_read_b128 v[218:221], v216 offset:20480
	ds_read_b128 v[222:225], v216 offset:21504
	ds_read_b128 v[226:229], v216 offset:22528
	ds_read_b128 v[230:233], v216 offset:23552
	global_load_lds_dwordx4 v[190:191], off
	s_add_i32 m0, s22, 0x2000
	v_lshl_add_u64 v[192:193], s[20:21], 0, v[160:161]
	s_add_u32 s20, s20, s38
	s_addc_u32 s21, s21, s39
	s_add_i32 s19, s19, s45
	global_load_lds_dwordx4 v[192:193], off
	v_lshl_add_u64 v[194:195], s[20:21], 0, v[156:157]
	s_mov_b32 m0, s19
	v_lshl_add_u64 v[200:201], s[20:21], 0, v[160:161]
	global_load_lds_dwordx4 v[194:195], off
	s_add_i32 m0, s19, 0x2000
	v_lshl_add_u64 v[202:203], s[14:15], 0, v[154:155]
	global_load_lds_dwordx4 v[200:201], off
	s_mov_b32 m0, s8
	v_lshl_add_u64 v[204:205], s[14:15], 0, v[158:159]
	global_load_lds_dwordx4 v[202:203], off
	s_mov_b32 m0, s9
	s_nop 0
	global_load_lds_dwordx4 v[204:205], off
	s_waitcnt vmcnt(8)
	s_waitcnt lgkmcnt(0)
	s_barrier
; #define PG8_STAGE(bufoff, gbase, voff) do { _Pragma("unroll") for (int _i = 0; _i < 2; ++_i) \
;         __builtin_amdgcn_global_load_lds((const unsigned*)((const char*)(gbase) + (voff)[_i]), (LAS unsigned*)(lds + (bufoff) + ldsw + _i * 8192), 16, 0, 0); } while (0)
; #define PG8_LDA(dst, b, h) do { _Pragma("unroll") for (int m = 0; m < 4; ++m) _Pragma("unroll") for (int k = 0; k < 2; ++k) dst[m][k] = *(const LAS bf16x8*)(lds + PG8_SA(b, h) + aoff + m * 2048 + k * 1024); } while (0)
; #define PG8_LDB(dst, b, h) do { _Pragma("unroll") for (int n = 0; n < 2; ++n) _Pragma("unroll") for (int k = 0; k < 2; ++k) dst[n][k] = *(const LAS bf16x8*)(lds + PG8_SB(b, h) + boff + n * 2048 + k * 1024); } while (0)
; #define PG8_MMA(ai, bj, At, Bt) do { __builtin_amdgcn_s_setprio(1); _Pragma("unroll") for (int m = 0; m < 4; ++m) _Pragma("unroll") for (int n = 0; n < 2; ++n) _Pragma("unroll") for (int k = 0; k < 2; ++k) \
;         acc[ai][bj][m][n] = __builtin_amdgcn_mfma_f32_16x16x32_bf16(Bt[n][k], At[m][k], acc[ai][bj][m][n], 0, 0, 0); __builtin_amdgcn_s_setprio(0); } while (0)
; #define PG8_WAIT_V(n) asm volatile("s_waitcnt vmcnt(" #n ")" ::: "memory")
; #define PG8_WAIT_L(n) asm volatile("s_waitcnt lgkmcnt(" #n ")" ::: "memory")
; #define PG8_BAR __builtin_amdgcn_s_barrier()
; #define PG8_SCHED __builtin_amdgcn_sched_barrier(0)
; template <class Epi>
; __device__ __forceinline__ void gemm_phase(LAS unsigned char* lds, const Gemm g, const Epi& E) {
;     ...
;             PG8_WAIT_V(8); PG8_WAIT_L(0); PG8_BAR; PG8_MMA(1, 0, At, B0); PG8_MMA(1, 1, At, B1); PG8_BAR; PG8_SCHED;
;             PG8_LDB(B0, 1, 0); PG8_LDB(B1, 1, 1); PG8_SCHED; PG8_LDA(At, 1, 0); PG8_STAGE(PG8_SA(0, 1), a2 + hstepA, voffA);
;             PG8_WAIT_V(8); PG8_WAIT_L(0); PG8_BAR; PG8_MMA(0, 0, At, B0); PG8_MMA(0, 1, At, B1); PG8_BAR; PG8_SCHED;
	s_setprio 1
	v_mfma_f32_16x16x32_bf16 v[60:63], v[130:133], v[174:177], v[60:63]
	v_mfma_f32_16x16x32_bf16 v[56:59], v[138:141], v[174:177], v[56:59]
	v_mfma_f32_16x16x32_bf16 v[44:47], v[130:133], v[182:185], v[44:47]
	v_mfma_f32_16x16x32_bf16 v[40:43], v[138:141], v[182:185], v[40:43]
	v_mfma_f32_16x16x32_bf16 v[28:31], v[130:133], v[218:221], v[28:31]
	v_mfma_f32_16x16x32_bf16 v[24:27], v[138:141], v[218:221], v[24:27]
	v_mfma_f32_16x16x32_bf16 v[12:15], v[130:133], v[226:229], v[12:15]
	v_mfma_f32_16x16x32_bf16 v[8:11], v[138:141], v[226:229], v[8:11]
	v_mfma_f32_16x16x32_bf16 v[60:63], v[134:137], v[178:181], v[60:63]
	v_mfma_f32_16x16x32_bf16 v[56:59], v[142:145], v[178:181], v[56:59]
	v_mfma_f32_16x16x32_bf16 v[44:47], v[134:137], v[186:189], v[44:47]
	v_mfma_f32_16x16x32_bf16 v[40:43], v[142:145], v[186:189], v[40:43]
	v_mfma_f32_16x16x32_bf16 v[28:31], v[134:137], v[222:225], v[28:31]
	v_mfma_f32_16x16x32_bf16 v[24:27], v[142:145], v[222:225], v[24:27]
	v_mfma_f32_16x16x32_bf16 v[12:15], v[134:137], v[230:233], v[12:15]
	v_mfma_f32_16x16x32_bf16 v[8:11], v[142:145], v[230:233], v[8:11]
	s_setprio 0
	s_setprio 1
	v_mfma_f32_16x16x32_bf16 v[52:55], v[146:149], v[174:177], v[52:55]
	v_mfma_f32_16x16x32_bf16 v[48:51], v[166:169], v[174:177], v[48:51]
	v_mfma_f32_16x16x32_bf16 v[36:39], v[146:149], v[182:185], v[36:39]
	v_mfma_f32_16x16x32_bf16 v[32:35], v[166:169], v[182:185], v[32:35]
	v_mfma_f32_16x16x32_bf16 v[20:23], v[146:149], v[218:221], v[20:23]
	v_mfma_f32_16x16x32_bf16 v[16:19], v[166:169], v[218:221], v[16:19]
	v_mfma_f32_16x16x32_bf16 v[4:7], v[146:149], v[226:229], v[4:7]
	v_mfma_f32_16x16x32_bf16 v[0:3], v[166:169], v[226:229], v[0:3]
	v_mfma_f32_16x16x32_bf16 v[52:55], v[150:153], v[178:181], v[52:55]
	v_mfma_f32_16x16x32_bf16 v[48:51], v[170:173], v[178:181], v[48:51]
	v_mfma_f32_16x16x32_bf16 v[36:39], v[150:153], v[186:189], v[36:39]
	v_mfma_f32_16x16x32_bf16 v[32:35], v[170:173], v[186:189], v[32:35]
	v_mfma_f32_16x16x32_bf16 v[20:23], v[150:153], v[222:225], v[20:23]
	v_mfma_f32_16x16x32_bf16 v[16:19], v[170:173], v[222:225], v[16:19]
	v_mfma_f32_16x16x32_bf16 v[4:7], v[150:153], v[230:233], v[4:7]
	v_mfma_f32_16x16x32_bf16 v[0:3], v[170:173], v[230:233], v[0:3]
	s_setprio 0
	s_barrier
	s_add_i32 s19, 0, 0x18000
	v_add_u32_e32 v96, s19, v213
	s_add_i32 s20, 0, 0x1c000
	ds_read_b128 v[130:133], v96
	ds_read_b128 v[134:137], v96 offset:1024
	ds_read_b128 v[138:141], v96 offset:2048
	ds_read_b128 v[142:145], v96 offset:3072
	v_add_u32_e32 v96, s20, v213
	ds_read_b128 v[146:149], v96
	ds_read_b128 v[150:153], v96 offset:1024
	ds_read_b128 v[166:169], v96 offset:2048
	ds_read_b128 v[170:173], v96 offset:3072
	s_add_u32 s14, s14, s38
	s_addc_u32 s15, s15, s39
	s_mov_b32 m0, s10
	v_lshl_add_u64 v[206:207], s[14:15], 0, v[154:155]
	ds_read_b128 v[174:177], v216 offset:32768
	ds_read_b128 v[178:181], v216 offset:33792
	ds_read_b128 v[182:185], v216 offset:34816
	ds_read_b128 v[186:189], v216 offset:35840
	ds_read_b128 v[218:221], v216 offset:36864
	ds_read_b128 v[222:225], v216 offset:37888
	ds_read_b128 v[226:229], v216 offset:38912
	ds_read_b128 v[230:233], v216 offset:39936
	global_load_lds_dwordx4 v[206:207], off
	v_lshl_add_u64 v[206:207], s[14:15], 0, v[158:159]
	s_mov_b32 m0, s11
	s_nop 0
	global_load_lds_dwordx4 v[206:207], off
	s_waitcnt vmcnt(8)
	s_waitcnt lgkmcnt(0)
	s_barrier
	s_setprio 1
	v_mfma_f32_16x16x32_bf16 v[126:129], v[130:133], v[174:177], v[126:129]
	v_mfma_f32_16x16x32_bf16 v[122:125], v[138:141], v[174:177], v[122:125]
	v_mfma_f32_16x16x32_bf16 v[110:113], v[130:133], v[182:185], v[110:113]
	v_mfma_f32_16x16x32_bf16 v[106:109], v[138:141], v[182:185], v[106:109]
	v_mfma_f32_16x16x32_bf16 v[92:95], v[130:133], v[218:221], v[92:95]
	v_mfma_f32_16x16x32_bf16 v[88:91], v[138:141], v[218:221], v[88:91]
	v_mfma_f32_16x16x32_bf16 v[76:79], v[130:133], v[226:229], v[76:79]
	v_mfma_f32_16x16x32_bf16 v[72:75], v[138:141], v[226:229], v[72:75]
	v_mfma_f32_16x16x32_bf16 v[126:129], v[134:137], v[178:181], v[126:129]
	v_mfma_f32_16x16x32_bf16 v[122:125], v[142:145], v[178:181], v[122:125]
	v_mfma_f32_16x16x32_bf16 v[110:113], v[134:137], v[186:189], v[110:113]
	v_mfma_f32_16x16x32_bf16 v[106:109], v[142:145], v[186:189], v[106:109]
	v_mfma_f32_16x16x32_bf16 v[92:95], v[134:137], v[222:225], v[92:95]
	v_mfma_f32_16x16x32_bf16 v[88:91], v[142:145], v[222:225], v[88:91]
	v_mfma_f32_16x16x32_bf16 v[76:79], v[134:137], v[230:233], v[76:79]
	v_mfma_f32_16x16x32_bf16 v[72:75], v[142:145], v[230:233], v[72:75]
	s_setprio 0
	s_setprio 1
	v_mfma_f32_16x16x32_bf16 v[118:121], v[146:149], v[174:177], v[118:121]
	v_mfma_f32_16x16x32_bf16 v[114:117], v[166:169], v[174:177], v[114:117]
	v_mfma_f32_16x16x32_bf16 v[102:105], v[146:149], v[182:185], v[102:105]
	v_mfma_f32_16x16x32_bf16 v[98:101], v[166:169], v[182:185], v[98:101]
	v_mfma_f32_16x16x32_bf16 v[84:87], v[146:149], v[218:221], v[84:87]
	v_mfma_f32_16x16x32_bf16 v[80:83], v[166:169], v[218:221], v[80:83]
	v_mfma_f32_16x16x32_bf16 v[68:71], v[146:149], v[226:229], v[68:71]
	v_mfma_f32_16x16x32_bf16 v[64:67], v[166:169], v[226:229], v[64:67]
	v_mfma_f32_16x16x32_bf16 v[118:121], v[150:153], v[178:181], v[118:121]
	v_mfma_f32_16x16x32_bf16 v[114:117], v[170:173], v[178:181], v[114:117]
	v_mfma_f32_16x16x32_bf16 v[102:105], v[150:153], v[186:189], v[102:105]
	v_mfma_f32_16x16x32_bf16 v[98:101], v[170:173], v[186:189], v[98:101]
	v_mfma_f32_16x16x32_bf16 v[84:87], v[150:153], v[222:225], v[84:87]
	v_mfma_f32_16x16x32_bf16 v[80:83], v[170:173], v[222:225], v[80:83]
	v_mfma_f32_16x16x32_bf16 v[68:71], v[150:153], v[230:233], v[68:71]
	v_mfma_f32_16x16x32_bf16 v[64:67], v[170:173], v[230:233], v[64:67]
	s_setprio 0
	s_barrier
; #define PG8_STAGE(bufoff, gbase, voff) do { _Pragma("unroll") for (int _i = 0; _i < 2; ++_i) \
;         __builtin_amdgcn_global_load_lds((const unsigned*)((const char*)(gbase) + (voff)[_i]), (LAS unsigned*)(lds + (bufoff) + ldsw + _i * 8192), 16, 0, 0); } while (0)
; #define PG8_LDA(dst, b, h) do { _Pragma("unroll") for (int m = 0; m < 4; ++m) _Pragma("unroll") for (int k = 0; k < 2; ++k) dst[m][k] = *(const LAS bf16x8*)(lds + PG8_SA(b, h) + aoff + m * 2048 + k * 1024); } while (0)
; #define PG8_MMA(ai, bj, At, Bt) do { __builtin_amdgcn_s_setprio(1); _Pragma("unroll") for (int m = 0; m < 4; ++m) _Pragma("unroll") for (int n = 0; n < 2; ++n) _Pragma("unroll") for (int k = 0; k < 2; ++k) \
;         acc[ai][bj][m][n] = __builtin_amdgcn_mfma_f32_16x16x32_bf16(Bt[n][k], At[m][k], acc[ai][bj][m][n], 0, 0, 0); __builtin_amdgcn_s_setprio(0); } while (0)
; #define PG8_WAIT_V(n) asm volatile("s_waitcnt vmcnt(" #n ")" ::: "memory")
; #define PG8_WAIT_L(n) asm volatile("s_waitcnt lgkmcnt(" #n ")" ::: "memory")
; #define PG8_BAR __builtin_amdgcn_s_barrier()
; #define PG8_SCHED __builtin_amdgcn_sched_barrier(0)
; template <class Epi>
; __device__ __forceinline__ void gemm_phase(LAS unsigned char* lds, const Gemm g, const Epi& E) {
;     ...
;             PG8_LDA(At, 1, 1); PG8_STAGE(PG8_SB(1, 0), b3, voffB); PG8_STAGE(PG8_SB(1, 1), b3 + hstepB, voffB); PG8_STAGE(PG8_SA(1, 0), a3, voffA);
;             PG8_WAIT_V(8); PG8_WAIT_L(0); PG8_BAR; PG8_MMA(1, 0, At, B0); PG8_MMA(1, 1, At, B1); PG8_BAR; PG8_SCHED;
;         }
;         if (wr == 0) PG8_BAR;
	s_add_i32 s14, s19, s45
	v_lshl_add_u64 v[190:191], v[190:191], 0, s[96:97]
	s_mov_b32 m0, s14
	ds_read_b128 v[174:177], v216 offset:49152
	ds_read_b128 v[178:181], v216 offset:50176
	ds_read_b128 v[182:185], v216 offset:51200
	ds_read_b128 v[186:189], v216 offset:52224
	ds_read_b128 v[218:221], v216 offset:53248
	ds_read_b128 v[222:225], v216 offset:54272
	ds_read_b128 v[226:229], v216 offset:55296
	ds_read_b128 v[230:233], v216 offset:56320
	global_load_lds_dwordx4 v[190:191], off
	v_lshl_add_u64 v[190:191], v[192:193], 0, s[96:97]
	s_add_i32 m0, s14, 0x2000
	s_add_i32 s14, s20, s45
	global_load_lds_dwordx4 v[190:191], off
	v_lshl_add_u64 v[190:191], v[194:195], 0, s[96:97]
	s_mov_b32 m0, s14
	s_nop 0
	global_load_lds_dwordx4 v[190:191], off
	v_lshl_add_u64 v[190:191], v[200:201], 0, s[96:97]
	s_add_i32 m0, s14, 0x2000
	s_nop 0
	global_load_lds_dwordx4 v[190:191], off
	v_lshl_add_u64 v[190:191], v[202:203], 0, s[96:97]
	s_mov_b32 m0, s76
	s_nop 0
	global_load_lds_dwordx4 v[190:191], off
	v_lshl_add_u64 v[190:191], v[204:205], 0, s[96:97]
	s_mov_b32 m0, s77
	s_nop 0
	global_load_lds_dwordx4 v[190:191], off
	s_waitcnt vmcnt(8)
	s_waitcnt lgkmcnt(0)
	s_barrier
	s_setprio 1
	v_mfma_f32_16x16x32_bf16 v[60:63], v[130:133], v[174:177], v[60:63]
	v_mfma_f32_16x16x32_bf16 v[56:59], v[138:141], v[174:177], v[56:59]
	v_mfma_f32_16x16x32_bf16 v[44:47], v[130:133], v[182:185], v[44:47]
	v_mfma_f32_16x16x32_bf16 v[40:43], v[138:141], v[182:185], v[40:43]
	v_mfma_f32_16x16x32_bf16 v[28:31], v[130:133], v[218:221], v[28:31]
	v_mfma_f32_16x16x32_bf16 v[24:27], v[138:141], v[218:221], v[24:27]
	v_mfma_f32_16x16x32_bf16 v[12:15], v[130:133], v[226:229], v[12:15]
	v_mfma_f32_16x16x32_bf16 v[8:11], v[138:141], v[226:229], v[8:11]
	v_mfma_f32_16x16x32_bf16 v[60:63], v[134:137], v[178:181], v[60:63]
	v_mfma_f32_16x16x32_bf16 v[56:59], v[142:145], v[178:181], v[56:59]
	v_mfma_f32_16x16x32_bf16 v[44:47], v[134:137], v[186:189], v[44:47]
	v_mfma_f32_16x16x32_bf16 v[40:43], v[142:145], v[186:189], v[40:43]
	v_mfma_f32_16x16x32_bf16 v[28:31], v[134:137], v[222:225], v[28:31]
	v_mfma_f32_16x16x32_bf16 v[24:27], v[142:145], v[222:225], v[24:27]
	v_mfma_f32_16x16x32_bf16 v[12:15], v[134:137], v[230:233], v[12:15]
	v_mfma_f32_16x16x32_bf16 v[8:11], v[142:145], v[230:233], v[8:11]
	s_setprio 0
	s_setprio 1
	v_mfma_f32_16x16x32_bf16 v[52:55], v[146:149], v[174:177], v[52:55]
	v_mfma_f32_16x16x32_bf16 v[48:51], v[166:169], v[174:177], v[48:51]
	v_mfma_f32_16x16x32_bf16 v[36:39], v[146:149], v[182:185], v[36:39]
	v_mfma_f32_16x16x32_bf16 v[32:35], v[166:169], v[182:185], v[32:35]
	v_mfma_f32_16x16x32_bf16 v[20:23], v[146:149], v[218:221], v[20:23]
	v_mfma_f32_16x16x32_bf16 v[16:19], v[166:169], v[218:221], v[16:19]
	v_mfma_f32_16x16x32_bf16 v[4:7], v[146:149], v[226:229], v[4:7]
	v_mfma_f32_16x16x32_bf16 v[0:3], v[166:169], v[226:229], v[0:3]
	v_mfma_f32_16x16x32_bf16 v[52:55], v[150:153], v[178:181], v[52:55]
	v_mfma_f32_16x16x32_bf16 v[48:51], v[170:173], v[178:181], v[48:51]
	v_mfma_f32_16x16x32_bf16 v[36:39], v[150:153], v[186:189], v[36:39]
	v_mfma_f32_16x16x32_bf16 v[32:35], v[170:173], v[186:189], v[32:35]
	v_mfma_f32_16x16x32_bf16 v[20:23], v[150:153], v[222:225], v[20:23]
	v_mfma_f32_16x16x32_bf16 v[16:19], v[170:173], v[222:225], v[16:19]
	v_mfma_f32_16x16x32_bf16 v[4:7], v[150:153], v[230:233], v[4:7]
	v_mfma_f32_16x16x32_bf16 v[0:3], v[170:173], v[230:233], v[0:3]
	s_setprio 0
	s_barrier
	s_add_u32 s2, s2, 0x100
	s_addc_u32 s3, s3, 0
	s_add_u32 s16, s16, 0x100
	s_addc_u32 s17, s17, 0
	s_cmp_ge_u32 s18, s84
	s_mov_b32 s14, s18
	s_cbranch_scc0 .LBB0_324
	v_readlane_b32 s2, v254, 49
	v_readlane_b32 s3, v254, 50
	s_and_b64 vcc, exec, s[2:3]
	s_cbranch_vccz .LBB0_328
	s_barrier
	s_cmp_lt_i32 s69, 2
	s_mov_b64 s[2:3], -1
	s_cbranch_scc0 .LBB0_329
